# placement test: older half loop head at 40 mod 64
# speedup vs baseline: 1.0199x; 1.0040x over previous
.LBB0_619:
	v_readfirstlane_b32 s12, v170
	s_lshr_b32 s12, s12, 6
	s_mul_i32 s12, s12, 12288
	s_add_i32 s12, s12, 45056
	v_and_b32_e32 v172, 63, v170
	v_lshl_add_u32 v172, v172, 2, s12
	ds_write_b32 v172, v202 offset:0
	ds_write_b32 v172, v203 offset:256
	ds_write_b32 v172, v204 offset:512
	ds_write_b32 v172, v205 offset:768
	ds_write_b32 v172, v206 offset:1024
	ds_write_b32 v172, v207 offset:1280
	ds_write_b32 v172, v208 offset:1536
	ds_write_b32 v172, v209 offset:1792
	ds_write_b32 v172, v210 offset:2048
	ds_write_b32 v172, v211 offset:2304
	ds_write_b32 v172, v212 offset:2560
	ds_write_b32 v172, v213 offset:2816
	ds_write_b32 v172, v214 offset:3072
	ds_write_b32 v172, v215 offset:3328
	ds_write_b32 v172, v216 offset:3584
	ds_write_b32 v172, v217 offset:3840
	ds_write_b32 v172, v218 offset:4096
	ds_write_b32 v172, v219 offset:4352
	ds_write_b32 v172, v220 offset:4608
	ds_write_b32 v172, v221 offset:4864
	ds_write_b32 v172, v222 offset:5120
	ds_write_b32 v172, v223 offset:5376
	ds_write_b32 v172, v224 offset:5632
	ds_write_b32 v172, v225 offset:5888
	ds_write_b32 v172, v226 offset:6144
	ds_write_b32 v172, v227 offset:6400
	ds_write_b32 v172, v228 offset:6656
	ds_write_b32 v172, v229 offset:6912
	ds_write_b32 v172, v230 offset:7168
	ds_write_b32 v172, v231 offset:7424
	ds_write_b32 v172, v232 offset:7680
	ds_write_b32 v172, v233 offset:7936
	ds_write_b32 v172, v234 offset:8192
	ds_write_b32 v172, v235 offset:8448
	ds_write_b32 v172, v236 offset:8704
	ds_write_b32 v172, v237 offset:8960
	ds_write_b32 v172, v238 offset:9216
	ds_write_b32 v172, v239 offset:9472
	ds_write_b32 v172, v240 offset:9728
	ds_write_b32 v172, v241 offset:9984
	ds_write_b32 v172, v242 offset:10240
	ds_write_b32 v172, v243 offset:10496
	ds_write_b32 v172, v244 offset:10752
	ds_write_b32 v172, v245 offset:11008
	ds_write_b32 v172, v246 offset:11264
	ds_write_b32 v172, v247 offset:11520
	ds_write_b32 v172, v248 offset:11776
	ds_write_b32 v172, v249 offset:12032
	s_waitcnt lgkmcnt(0)
	v_mul_u32_u24_e32 v1, 0xd0, v162
	v_lshlrev_b32_e32 v0, 4, v161
	v_add_u32_e32 v112, v1, v0
	v_lshlrev_b32_e32 v36, 6, v162
	v_sub_u32_e32 v176, v112, v36
	s_movk_i32 s13, 0x80
	s_cmp_lt_i32 s21, 1
	s_cselect_b32 s12, 0x2080, s13
	s_movk_i32 s13, 0x600
	v_add_u32_e32 v48, s12, v163
	v_mad_i64_i32 v[150:151], s[14:15], v48, s13, v[150:151]
	v_add_u32_e32 v48, s12, v164
	v_mad_i64_i32 v[154:155], s[14:15], v48, s13, v[154:155]
	s_lshl_b32 s12, s12, 1
	s_mov_b32 s13, 0
	v_lshl_add_u64 v[152:153], v[152:153], 0, s[12:13]
	s_mov_b32 s26, 0x18000
	s_mov_b32 s27, 0
	s_movk_i32 s30, 0x80
	s_mov_b32 s31, 0
	s_mov_b32 s14, 0xff800000
	s_mov_b32 s15, 0xff800000
	s_mov_b32 s28, 0
	v_mov_b32_e32 v0, 0
	v_mov_b32_e32 v1, 0
	v_mov_b32_e32 v2, 0
	v_mov_b32_e32 v3, 0
	v_mov_b32_e32 v4, 0
	v_mov_b32_e32 v5, 0
	v_mov_b32_e32 v6, 0
	v_mov_b32_e32 v7, 0
	v_mov_b32_e32 v8, 0
	v_mov_b32_e32 v9, 0
	v_mov_b32_e32 v10, 0
	v_mov_b32_e32 v11, 0
	v_mov_b32_e32 v12, 0
	v_mov_b32_e32 v13, 0
	v_mov_b32_e32 v14, 0
	v_mov_b32_e32 v15, 0
	v_mov_b32_e32 v16, 0
	v_mov_b32_e32 v17, 0
	v_mov_b32_e32 v18, 0
	v_mov_b32_e32 v19, 0
	v_mov_b32_e32 v20, 0
	v_mov_b32_e32 v21, 0
	v_mov_b32_e32 v22, 0
	v_mov_b32_e32 v23, 0
	v_mov_b32_e32 v24, 0
	v_mov_b32_e32 v25, 0
	v_mov_b32_e32 v26, 0
	v_mov_b32_e32 v27, 0
	v_mov_b32_e32 v28, 0
	v_mov_b32_e32 v29, 0
	v_mov_b32_e32 v30, 0
	v_mov_b32_e32 v31, 0
	v_mov_b32_e32 v32, 0
	v_mov_b32_e32 v33, 0
	v_mov_b32_e32 v34, 0
	v_mov_b32_e32 v35, 0
	v_mov_b32_e32 v36, 0
	v_mov_b32_e32 v37, 0
	v_mov_b32_e32 v38, 0
	v_mov_b32_e32 v39, 0
	v_mov_b32_e32 v40, 0
	v_mov_b32_e32 v41, 0
	v_mov_b32_e32 v42, 0
	v_mov_b32_e32 v43, 0
	v_mov_b32_e32 v44, 0
	v_mov_b32_e32 v45, 0
	v_mov_b32_e32 v46, 0
	v_mov_b32_e32 v47, 0
	v_mov_b32_e32 v156, 0
	v_mov_b32_e32 v157, 0
	v_readfirstlane_b32 s12, v170
	s_cmpk_ge_u32 s12, 0x100
	s_cbranch_scc1 .Lmla_B_entry
	.p2align	6
	s_nop 0
	s_nop 0
	s_nop 0
	s_nop 0
	s_nop 0
	s_nop 0
	s_nop 0
	s_nop 0
	s_nop 0
	s_nop 0
